# speedup vs baseline: 1.0019x; 1.0019x over previous
;   __device__ __forceinline__ u16* hbuf() const { return (u16*)(ws + 57 * MB); }
; #define WAIT_V(n) asm volatile("s_waitcnt vmcnt(%0)" ::"n"(n) : "memory")
; #define WAIT_L(n) asm volatile("s_waitcnt lgkmcnt(%0)" ::"n"(n) : "memory")
; #define BAR8 __builtin_amdgcn_s_barrier()
; template <int EPI> ...
;     ...
;       if (wr == 1) BAR8;
;       BAR8;
;       STAGE_Bm(1, 0, Bb, 1); STAGE_A(1, 0, Ab, 1); STAGE_Bm(1, 1, Bb, 1);
;       WAIT_V(6); BAR8;
; #pragma unroll 1
;       for (int t0_ = 0; t0_ < nt - 2; t0_ += 2) {
;         if constexpr (EPI == EPI_M0) {
;           if (t0_ == 8) {
;             int tid_s = tid;
;             asm volatile("" : "+v"(tid_s));
;             const int wid = tid_s >> 6, lane = tid_s & 63, wr = wid >> 2, wc = wid & 3, fr = lane & 15, fq = lane >> 4;
;             char* wsn = shm + 131072 + wid * 4096;
;             u16* sout = p.hbuf() + (long)(pm * 256 + wr * 128 + (lane >> 3)) * DM + pn * 256 + wc * 64 + (lane & 7) * 8;
; #pragma unroll
;             for (int qd = 0; qd < 4; ++qd) {
; #pragma unroll
;               for (int mm = 0; mm < 2; ++mm)
; #pragma unroll
;                 for (int n = 0; n < 4; ++n) {
;                   const f32x4 v = acc[qd * 2 + mm][n];
;                   u32x2 o = {pack2(v[0], v[1]), pack2(v[2], v[3])};
;                   *(u32x2*)(wsn + (mm * 16 + fr) * 128 + (((n * 2 + (fq >> 1)) ^ (fr & 7)) << 4) + (fq & 1) * 8) = o;
;                 }
;               asm volatile("s_waitcnt lgkmcnt(0)" ::: "memory");
; #pragma unroll
;               for (int i = 0; i < 4; ++i) {
;                 const u32x4 d = *(const u32x4*)(wsn + (i * 8 + (lane >> 3)) * 128 + (((lane & 7) ^ ((lane >> 3) & 7)) << 4));
;                 *(u32x4*)(sout + (long)(qd * 32 + i * 8) * DM) = d;
;               }
;               asm volatile("s_waitcnt lgkmcnt(0)" ::: "memory");
;             }
;           }
;         }
;         int t = t0_;
;         asm volatile("" : "+s"(t));
;         LDB8(B0, 0, 0); SCHED8; LDA8(At, 0, 0); STAGE_A(1, 1, Ab, t + 1);
;         WAIT_L(8); BAR8; WAIT_L(0); MMA8(0, 0, At, B0); BAR8; SCHED8;
;         LDB8(B1, 0, 1); STAGE_Bm(0, 0, Bb, t + 2);
;         BAR8; WAIT_L(0); MMA8(0, 1, At, B1); BAR8;
;         LDA8(At, 0, 1); STAGE_A(0, 0, Ab, t + 2);
;         BAR8; WAIT_L(0); MMA8(1, 0, At, B0); BAR8; SCHED8;
;         STAGE_Bm(0, 1, Bb, t + 2);
;         WAIT_V(6); BAR8; MMA8(1, 1, At, B1); BAR8;
.LBB0_139:
	s_or_b64 exec, exec, s[22:23]
	v_lshl_add_u64 v[138:139], s[6:7], 0, v[4:5]
	s_mov_b64 s[6:7], 0x80
	s_mov_b32 m0, s57
	v_lshl_add_u64 v[8:9], v[138:139], 0, s[6:7]
	s_mov_b64 s[22:23], 0x40080
	s_barrier
	global_load_lds_dwordx4 v[8:9], off
	v_lshl_add_u64 v[8:9], v[138:139], 0, s[22:23]
	s_mov_b32 m0, s58
	v_lshl_add_u64 v[136:137], s[16:17], 0, v[0:1]
	global_load_lds_dwordx4 v[8:9], off
	v_lshl_add_u64 v[8:9], v[136:137], 0, s[6:7]
	s_mov_b32 m0, s59
	s_mov_b64 s[6:7], 0x10080
	global_load_lds_dwordx4 v[8:9], off
	v_lshl_add_u64 v[8:9], v[136:137], 0, s[22:23]
	s_mov_b32 m0, s65
	s_mov_b64 s[34:35], 0x40080
	global_load_lds_dwordx4 v[8:9], off
	v_lshl_add_u64 v[8:9], v[138:139], 0, s[6:7]
	s_mov_b32 m0, s70
	s_mov_b64 s[6:7], 0x50080
	global_load_lds_dwordx4 v[8:9], off
	v_lshl_add_u64 v[8:9], v[138:139], 0, s[6:7]
	s_mov_b32 m0, s71
	s_mov_b64 s[6:7], 0x20000
	global_load_lds_dwordx4 v[8:9], off
	v_lshl_add_u64 v[140:141], v[136:137], 0, s[6:7]
	v_lshl_add_u64 v[142:143], v[138:139], 0, s[44:45]
	s_mov_b32 s16, -2
	s_barrier
	s_add_i32 s16, s16, 2
	s_mov_b32 s6, s16
	ds_read_b128 v[144:147], v154 offset:32768
	ds_read_b128 v[148:151], v154 offset:33792
	ds_read_b128 v[172:175], v154 offset:34816
	ds_read_b128 v[176:179], v154 offset:35840
	s_lshl_b32 s94, s6, 6
	s_add_i32 s6, s94, 64
	s_ashr_i32 s7, s6, 31
	s_add_i32 s93, s55, 0x14000
	v_lshl_add_u64 v[152:153], s[6:7], 1, v[140:141]
	s_mov_b32 m0, s93
	ds_read_b128 v[186:189], v7
	ds_read_b128 v[190:193], v7 offset:1024
	ds_read_b128 v[194:197], v7 offset:2048
	ds_read_b128 v[198:201], v7 offset:3072
	ds_read_b128 v[202:205], v7 offset:4096
	ds_read_b128 v[206:209], v7 offset:5120
	ds_read_b128 v[210:213], v7 offset:6144
	ds_read_b128 v[214:217], v7 offset:7168
	global_load_lds_dwordx4 v[152:153], off
	v_lshl_add_u64 v[152:153], v[152:153], 0, s[62:63]
	s_mov_b32 m0, s72
	s_nop 0
	global_load_lds_dwordx4 v[152:153], off
	s_waitcnt lgkmcnt(8)
	s_barrier
	s_waitcnt lgkmcnt(0)
	s_setprio 1
	s_waitcnt lgkmcnt(0)
	v_mfma_f32_16x16x32_bf16 v[132:135], v[144:147], v[186:189], 0
	v_mfma_f32_16x16x32_bf16 v[128:131], v[172:175], v[186:189], 0
	v_mfma_f32_16x16x32_bf16 v[116:119], v[144:147], v[194:197], 0
	v_mfma_f32_16x16x32_bf16 v[108:111], v[172:175], v[194:197], 0
	v_mfma_f32_16x16x32_bf16 v[72:75], v[144:147], v[202:205], 0
	v_mfma_f32_16x16x32_bf16 v[64:67], v[172:175], v[202:205], 0
	v_mfma_f32_16x16x32_bf16 v[36:39], v[144:147], v[210:213], 0
	v_mfma_f32_16x16x32_bf16 v[24:27], v[172:175], v[210:213], 0
	v_mfma_f32_16x16x32_bf16 v[132:135], v[148:151], v[190:193], v[132:135]
	v_mfma_f32_16x16x32_bf16 v[128:131], v[176:179], v[190:193], v[128:131]
	v_mfma_f32_16x16x32_bf16 v[116:119], v[148:151], v[198:201], v[116:119]
	v_mfma_f32_16x16x32_bf16 v[108:111], v[176:179], v[198:201], v[108:111]
	v_mfma_f32_16x16x32_bf16 v[72:75], v[148:151], v[206:209], v[72:75]
	v_mfma_f32_16x16x32_bf16 v[64:67], v[176:179], v[206:209], v[64:67]
	v_mfma_f32_16x16x32_bf16 v[36:39], v[148:151], v[214:217], v[36:39]
	v_mfma_f32_16x16x32_bf16 v[24:27], v[176:179], v[214:217], v[24:27]
	s_setprio 0
	s_barrier
	s_add_i32 s6, s94, 0x80
	s_ashr_i32 s7, s6, 31
	s_lshl_b64 s[6:7], s[6:7], 1
	s_add_i32 s22, s55, 0x8000
	v_lshl_add_u64 v[152:153], v[138:139], 0, s[6:7]
	s_mov_b32 m0, s22
	s_add_i32 s17, s55, 0xa000
	ds_read_b128 v[218:221], v154 offset:49152
	ds_read_b128 v[222:225], v154 offset:50176
	ds_read_b128 v[226:229], v154 offset:51200
	ds_read_b128 v[230:233], v154 offset:52224
	global_load_lds_dwordx4 v[152:153], off
	v_lshl_add_u64 v[152:153], v[152:153], 0, s[62:63]
	s_mov_b32 m0, s17
	s_nop 0
	global_load_lds_dwordx4 v[152:153], off
	s_barrier
	s_waitcnt lgkmcnt(0)
	s_setprio 1
	s_waitcnt lgkmcnt(0)
	v_mfma_f32_16x16x32_bf16 v[92:95], v[218:221], v[186:189], 0
	v_mfma_f32_16x16x32_bf16 v[76:79], v[226:229], v[186:189], 0
	v_mfma_f32_16x16x32_bf16 v[44:47], v[218:221], v[194:197], 0
	v_mfma_f32_16x16x32_bf16 v[40:43], v[226:229], v[194:197], 0
	v_mfma_f32_16x16x32_bf16 v[20:23], v[218:221], v[202:205], 0
	v_mfma_f32_16x16x32_bf16 v[16:19], v[226:229], v[202:205], 0
	v_mfma_f32_16x16x32_bf16 v[12:15], v[218:221], v[210:213], 0
	v_mfma_f32_16x16x32_bf16 v[8:11], v[226:229], v[210:213], 0
	v_mfma_f32_16x16x32_bf16 v[92:95], v[222:225], v[190:193], v[92:95]
	v_mfma_f32_16x16x32_bf16 v[76:79], v[230:233], v[190:193], v[76:79]
	v_mfma_f32_16x16x32_bf16 v[44:47], v[222:225], v[198:201], v[44:47]
	v_mfma_f32_16x16x32_bf16 v[40:43], v[230:233], v[198:201], v[40:43]
	v_mfma_f32_16x16x32_bf16 v[20:23], v[222:225], v[206:209], v[20:23]
	v_mfma_f32_16x16x32_bf16 v[16:19], v[230:233], v[206:209], v[16:19]
	v_mfma_f32_16x16x32_bf16 v[12:15], v[222:225], v[214:217], v[12:15]
	v_mfma_f32_16x16x32_bf16 v[8:11], v[230:233], v[214:217], v[8:11]
	s_setprio 0
	s_mov_b32 m0, s55
	v_lshl_add_u64 v[152:153], v[136:137], 0, s[6:7]
	s_add_i32 s23, s55, 0x2000
	s_barrier
	ds_read_b128 v[186:189], v7 offset:16384
	ds_read_b128 v[190:193], v7 offset:17408
	ds_read_b128 v[194:197], v7 offset:18432
	ds_read_b128 v[198:201], v7 offset:19456
	ds_read_b128 v[202:205], v7 offset:20480
	ds_read_b128 v[206:209], v7 offset:21504
	ds_read_b128 v[210:213], v7 offset:22528
	ds_read_b128 v[214:217], v7 offset:23552
	global_load_lds_dwordx4 v[152:153], off
	v_lshl_add_u64 v[152:153], v[152:153], 0, s[62:63]
	s_mov_b32 m0, s23
	s_nop 0
	global_load_lds_dwordx4 v[152:153], off
	s_barrier
; #define WAIT_V(n) asm volatile("s_waitcnt vmcnt(%0)" ::"n"(n) : "memory")
; #define LDA8(dst, b, h)                                                                                              \
;   _Pragma("unroll") for (int m_ = 0; m_ < 4; ++m_) _Pragma("unroll") for (int k_ = 0; k_ < 2; ++k_)                  \
;     dst[m_][k_] = *(const bf16x8*)(shm + SLOT_A(b, h) + abase8 + m_ * 2048 + k_ * 1024)
; #define LDB8(dst, b, h)                                                                                              \
;   _Pragma("unroll") for (int n_ = 0; n_ < 2; ++n_) _Pragma("unroll") for (int k_ = 0; k_ < 2; ++k_)                  \
;     dst[n_][k_] = *(const bf16x8*)(shm + SLOT_B(b, h) + bbase8 + n_ * 2048 + k_ * 1024)
; #define WAIT_L(n) asm volatile("s_waitcnt lgkmcnt(%0)" ::"n"(n) : "memory")
; #define BAR8 __builtin_amdgcn_s_barrier()
; #define SCHED8 __builtin_amdgcn_sched_barrier(0)
; template <int EPI> ...
;     ...
;         BAR8; WAIT_L(0); MMA8(0, 1, At, B1); BAR8;
;         LDA8(At, 0, 1); STAGE_A(0, 0, Ab, t + 2);
;         BAR8; WAIT_L(0); MMA8(1, 0, At, B0); BAR8; SCHED8;
;         STAGE_Bm(0, 1, Bb, t + 2);
;         WAIT_V(6); BAR8; MMA8(1, 1, At, B1); BAR8;
;         LDB8(B0, 1, 0); SCHED8; LDA8(At, 1, 0); STAGE_A(0, 1, Ab, t + 2);
;         WAIT_L(8); BAR8; WAIT_L(0); MMA8(0, 0, At, B0); BAR8; SCHED8;
;         LDB8(B1, 1, 1); STAGE_Bm(1, 0, Bb, t + 3);
	s_waitcnt lgkmcnt(0)
	s_setprio 1
	s_waitcnt lgkmcnt(0)
	v_mfma_f32_16x16x32_bf16 v[48:51], v[144:147], v[186:189], 0
	v_mfma_f32_16x16x32_bf16 v[56:59], v[172:175], v[186:189], 0
	v_mfma_f32_16x16x32_bf16 v[68:71], v[144:147], v[194:197], 0
	v_mfma_f32_16x16x32_bf16 v[84:87], v[172:175], v[194:197], 0
	v_mfma_f32_16x16x32_bf16 v[96:99], v[144:147], v[202:205], 0
	v_mfma_f32_16x16x32_bf16 v[104:107], v[172:175], v[202:205], 0
	v_mfma_f32_16x16x32_bf16 v[120:123], v[144:147], v[210:213], 0
	v_mfma_f32_16x16x32_bf16 v[124:127], v[172:175], v[210:213], 0
	v_mfma_f32_16x16x32_bf16 v[48:51], v[148:151], v[190:193], v[48:51]
	v_mfma_f32_16x16x32_bf16 v[56:59], v[176:179], v[190:193], v[56:59]
	v_mfma_f32_16x16x32_bf16 v[68:71], v[148:151], v[198:201], v[68:71]
	v_mfma_f32_16x16x32_bf16 v[84:87], v[176:179], v[198:201], v[84:87]
	v_mfma_f32_16x16x32_bf16 v[96:99], v[148:151], v[206:209], v[96:99]
	v_mfma_f32_16x16x32_bf16 v[104:107], v[176:179], v[206:209], v[104:107]
	v_mfma_f32_16x16x32_bf16 v[120:123], v[148:151], v[214:217], v[120:123]
	v_mfma_f32_16x16x32_bf16 v[124:127], v[176:179], v[214:217], v[124:127]
	s_setprio 0
	s_barrier
	s_add_i32 s25, s55, 0xc000
	v_lshl_add_u64 v[144:145], v[142:143], 0, s[6:7]
	s_mov_b32 m0, s25
	s_add_i32 s90, s55, 0xe000
	global_load_lds_dwordx4 v[144:145], off
	v_lshl_add_u64 v[144:145], v[144:145], 0, s[62:63]
	s_mov_b32 m0, s90
	s_nop 0
	global_load_lds_dwordx4 v[144:145], off
	s_waitcnt vmcnt(6)
	s_barrier
	s_setprio 1
	v_mfma_f32_16x16x32_bf16 v[28:31], v[218:221], v[186:189], 0
	v_mfma_f32_16x16x32_bf16 v[32:35], v[226:229], v[186:189], 0
	v_mfma_f32_16x16x32_bf16 v[52:55], v[218:221], v[194:197], 0
	v_mfma_f32_16x16x32_bf16 v[60:63], v[226:229], v[194:197], 0
	v_mfma_f32_16x16x32_bf16 v[80:83], v[218:221], v[202:205], 0
	v_mfma_f32_16x16x32_bf16 v[88:91], v[226:229], v[202:205], 0
	v_mfma_f32_16x16x32_bf16 v[100:103], v[218:221], v[210:213], 0
	v_mfma_f32_16x16x32_bf16 v[112:115], v[226:229], v[210:213], 0
	v_mfma_f32_16x16x32_bf16 v[28:31], v[222:225], v[190:193], v[28:31]
	v_mfma_f32_16x16x32_bf16 v[32:35], v[230:233], v[190:193], v[32:35]
	v_mfma_f32_16x16x32_bf16 v[52:55], v[222:225], v[198:201], v[52:55]
	v_mfma_f32_16x16x32_bf16 v[60:63], v[230:233], v[198:201], v[60:63]
	v_mfma_f32_16x16x32_bf16 v[80:83], v[222:225], v[206:209], v[80:83]
	v_mfma_f32_16x16x32_bf16 v[88:91], v[230:233], v[206:209], v[88:91]
	v_mfma_f32_16x16x32_bf16 v[100:103], v[222:225], v[214:217], v[100:103]
	v_mfma_f32_16x16x32_bf16 v[112:115], v[230:233], v[214:217], v[112:115]
	s_setprio 0
	s_barrier
	ds_read_b128 v[144:147], v156
	ds_read_b128 v[148:151], v157
	ds_read_b128 v[172:175], v158
	ds_read_b128 v[176:179], v159
	s_add_i32 s91, s55, 0x4000
	v_lshl_add_u64 v[152:153], v[140:141], 0, s[6:7]
	s_mov_b32 m0, s91
	s_add_i32 s92, s55, 0x6000
	ds_read_b128 v[186:189], v162
	ds_read_b128 v[190:193], v162 offset:1024
	ds_read_b128 v[194:197], v162 offset:2048
	ds_read_b128 v[198:201], v162 offset:3072
	ds_read_b128 v[202:205], v162 offset:4096
	ds_read_b128 v[206:209], v162 offset:5120
	ds_read_b128 v[210:213], v162 offset:6144
	ds_read_b128 v[214:217], v162 offset:7168
	global_load_lds_dwordx4 v[152:153], off
	v_lshl_add_u64 v[152:153], v[152:153], 0, s[62:63]
	s_mov_b32 m0, s92
	s_nop 0
	global_load_lds_dwordx4 v[152:153], off
	s_waitcnt lgkmcnt(8)
	s_barrier
	s_waitcnt lgkmcnt(0)
	s_setprio 1
	s_waitcnt lgkmcnt(0)
	v_mfma_f32_16x16x32_bf16 v[132:135], v[144:147], v[186:189], v[132:135]
	v_mfma_f32_16x16x32_bf16 v[128:131], v[172:175], v[186:189], v[128:131]
	v_mfma_f32_16x16x32_bf16 v[116:119], v[144:147], v[194:197], v[116:119]
	v_mfma_f32_16x16x32_bf16 v[108:111], v[172:175], v[194:197], v[108:111]
	v_mfma_f32_16x16x32_bf16 v[72:75], v[144:147], v[202:205], v[72:75]
	v_mfma_f32_16x16x32_bf16 v[64:67], v[172:175], v[202:205], v[64:67]
	v_mfma_f32_16x16x32_bf16 v[36:39], v[144:147], v[210:213], v[36:39]
	v_mfma_f32_16x16x32_bf16 v[24:27], v[172:175], v[210:213], v[24:27]
	v_mfma_f32_16x16x32_bf16 v[132:135], v[148:151], v[190:193], v[132:135]
	v_mfma_f32_16x16x32_bf16 v[128:131], v[176:179], v[190:193], v[128:131]
	v_mfma_f32_16x16x32_bf16 v[116:119], v[148:151], v[198:201], v[116:119]
	v_mfma_f32_16x16x32_bf16 v[108:111], v[176:179], v[198:201], v[108:111]
	v_mfma_f32_16x16x32_bf16 v[72:75], v[148:151], v[206:209], v[72:75]
	v_mfma_f32_16x16x32_bf16 v[64:67], v[176:179], v[206:209], v[64:67]
	v_mfma_f32_16x16x32_bf16 v[36:39], v[148:151], v[214:217], v[36:39]
	v_mfma_f32_16x16x32_bf16 v[24:27], v[176:179], v[214:217], v[24:27]
	s_setprio 0
	s_barrier
; #define WAIT_V(n) asm volatile("s_waitcnt vmcnt(%0)" ::"n"(n) : "memory")
; #define LDA8(dst, b, h)                                                                                              \
;   _Pragma("unroll") for (int m_ = 0; m_ < 4; ++m_) _Pragma("unroll") for (int k_ = 0; k_ < 2; ++k_)                  \
;     dst[m_][k_] = *(const bf16x8*)(shm + SLOT_A(b, h) + abase8 + m_ * 2048 + k_ * 1024)
; #define LDB8(dst, b, h)                                                                                              \
;   _Pragma("unroll") for (int n_ = 0; n_ < 2; ++n_) _Pragma("unroll") for (int k_ = 0; k_ < 2; ++k_)                  \
;     dst[n_][k_] = *(const bf16x8*)(shm + SLOT_B(b, h) + bbase8 + n_ * 2048 + k_ * 1024)
; #define WAIT_L(n) asm volatile("s_waitcnt lgkmcnt(%0)" ::"n"(n) : "memory")
; #define BAR8 __builtin_amdgcn_s_barrier()
; #define SCHED8 __builtin_amdgcn_sched_barrier(0)
; template <int EPI> ...
;     ...
;         LDB8(B0, 1, 0); SCHED8; LDA8(At, 1, 0); STAGE_A(0, 1, Ab, t + 2);
;         WAIT_L(8); BAR8; WAIT_L(0); MMA8(0, 0, At, B0); BAR8; SCHED8;
;         LDB8(B1, 1, 1); STAGE_Bm(1, 0, Bb, t + 3);
;         BAR8; WAIT_L(0); MMA8(0, 1, At, B1); BAR8;
;         LDA8(At, 1, 1); STAGE_A(1, 0, Ab, t + 3);
;         BAR8; WAIT_L(0); MMA8(1, 0, At, B0); BAR8; SCHED8;
;         STAGE_Bm(1, 1, Bb, t + 3);
;         WAIT_V(6); BAR8; MMA8(1, 1, At, B1); BAR8;
	s_add_i32 s6, s94, 0xc0
	s_ashr_i32 s7, s6, 31
	s_lshl_b64 s[6:7], s[6:7], 1
	s_mov_b32 m0, s57
	v_lshl_add_u64 v[152:153], v[138:139], 0, s[6:7]
	ds_read_b128 v[218:221], v164
	ds_read_b128 v[222:225], v166
	ds_read_b128 v[226:229], v168
	ds_read_b128 v[230:233], v170
	global_load_lds_dwordx4 v[152:153], off
	v_lshl_add_u64 v[152:153], v[152:153], 0, s[62:63]
	s_mov_b32 m0, s58
	s_nop 0
	global_load_lds_dwordx4 v[152:153], off
	s_barrier
	s_waitcnt lgkmcnt(0)
	s_setprio 1
	s_waitcnt lgkmcnt(0)
	v_mfma_f32_16x16x32_bf16 v[92:95], v[218:221], v[186:189], v[92:95]
	v_mfma_f32_16x16x32_bf16 v[76:79], v[226:229], v[186:189], v[76:79]
	v_mfma_f32_16x16x32_bf16 v[44:47], v[218:221], v[194:197], v[44:47]
	v_mfma_f32_16x16x32_bf16 v[40:43], v[226:229], v[194:197], v[40:43]
	v_mfma_f32_16x16x32_bf16 v[20:23], v[218:221], v[202:205], v[20:23]
	v_mfma_f32_16x16x32_bf16 v[16:19], v[226:229], v[202:205], v[16:19]
	v_mfma_f32_16x16x32_bf16 v[12:15], v[218:221], v[210:213], v[12:15]
	v_mfma_f32_16x16x32_bf16 v[8:11], v[226:229], v[210:213], v[8:11]
	v_mfma_f32_16x16x32_bf16 v[92:95], v[222:225], v[190:193], v[92:95]
	v_mfma_f32_16x16x32_bf16 v[76:79], v[230:233], v[190:193], v[76:79]
	v_mfma_f32_16x16x32_bf16 v[44:47], v[222:225], v[198:201], v[44:47]
	v_mfma_f32_16x16x32_bf16 v[40:43], v[230:233], v[198:201], v[40:43]
	v_mfma_f32_16x16x32_bf16 v[20:23], v[222:225], v[206:209], v[20:23]
	v_mfma_f32_16x16x32_bf16 v[16:19], v[230:233], v[206:209], v[16:19]
	v_mfma_f32_16x16x32_bf16 v[12:15], v[222:225], v[214:217], v[12:15]
	v_mfma_f32_16x16x32_bf16 v[8:11], v[230:233], v[214:217], v[8:11]
	s_setprio 0
	s_mov_b32 m0, s59
	v_lshl_add_u64 v[152:153], v[136:137], 0, s[6:7]
	s_barrier
	ds_read_b128 v[186:189], v171
	ds_read_b128 v[190:193], v171 offset:1024
	ds_read_b128 v[194:197], v171 offset:2048
	ds_read_b128 v[198:201], v171 offset:3072
	ds_read_b128 v[202:205], v171 offset:4096
	ds_read_b128 v[206:209], v171 offset:5120
	ds_read_b128 v[210:213], v171 offset:6144
	ds_read_b128 v[214:217], v171 offset:7168
	global_load_lds_dwordx4 v[152:153], off
	v_lshl_add_u64 v[152:153], v[152:153], 0, s[62:63]
	s_mov_b32 m0, s65
	s_nop 0
	global_load_lds_dwordx4 v[152:153], off
	s_barrier
	s_waitcnt lgkmcnt(0)
	s_setprio 1
	s_waitcnt lgkmcnt(0)
	v_mfma_f32_16x16x32_bf16 v[48:51], v[144:147], v[186:189], v[48:51]
	v_mfma_f32_16x16x32_bf16 v[56:59], v[172:175], v[186:189], v[56:59]
	v_mfma_f32_16x16x32_bf16 v[68:71], v[144:147], v[194:197], v[68:71]
	v_mfma_f32_16x16x32_bf16 v[84:87], v[172:175], v[194:197], v[84:87]
	v_mfma_f32_16x16x32_bf16 v[96:99], v[144:147], v[202:205], v[96:99]
	v_mfma_f32_16x16x32_bf16 v[104:107], v[172:175], v[202:205], v[104:107]
	v_mfma_f32_16x16x32_bf16 v[120:123], v[144:147], v[210:213], v[120:123]
	v_mfma_f32_16x16x32_bf16 v[124:127], v[172:175], v[210:213], v[124:127]
	v_mfma_f32_16x16x32_bf16 v[48:51], v[148:151], v[190:193], v[48:51]
	v_mfma_f32_16x16x32_bf16 v[56:59], v[176:179], v[190:193], v[56:59]
	v_mfma_f32_16x16x32_bf16 v[68:71], v[148:151], v[198:201], v[68:71]
	v_mfma_f32_16x16x32_bf16 v[84:87], v[176:179], v[198:201], v[84:87]
	v_mfma_f32_16x16x32_bf16 v[96:99], v[148:151], v[206:209], v[96:99]
	v_mfma_f32_16x16x32_bf16 v[104:107], v[176:179], v[206:209], v[104:107]
	v_mfma_f32_16x16x32_bf16 v[120:123], v[148:151], v[214:217], v[120:123]
	v_mfma_f32_16x16x32_bf16 v[124:127], v[176:179], v[214:217], v[124:127]
	s_setprio 0
	s_barrier
	s_mov_b32 m0, s70
	v_lshl_add_u64 v[144:145], v[142:143], 0, s[6:7]
	global_load_lds_dwordx4 v[144:145], off
	v_lshl_add_u64 v[144:145], v[144:145], 0, s[62:63]
	s_mov_b32 m0, s71
	s_nop 0
	global_load_lds_dwordx4 v[144:145], off
	s_waitcnt vmcnt(6)
	s_barrier
	s_setprio 1
	v_mfma_f32_16x16x32_bf16 v[28:31], v[218:221], v[186:189], v[28:31]
	v_mfma_f32_16x16x32_bf16 v[32:35], v[226:229], v[186:189], v[32:35]
	v_mfma_f32_16x16x32_bf16 v[52:55], v[218:221], v[194:197], v[52:55]
	v_mfma_f32_16x16x32_bf16 v[60:63], v[226:229], v[194:197], v[60:63]
	v_mfma_f32_16x16x32_bf16 v[80:83], v[218:221], v[202:205], v[80:83]
	v_mfma_f32_16x16x32_bf16 v[88:91], v[226:229], v[202:205], v[88:91]
	v_mfma_f32_16x16x32_bf16 v[100:103], v[218:221], v[210:213], v[100:103]
	v_mfma_f32_16x16x32_bf16 v[112:115], v[226:229], v[210:213], v[112:115]
	v_mfma_f32_16x16x32_bf16 v[28:31], v[222:225], v[190:193], v[28:31]
	v_mfma_f32_16x16x32_bf16 v[32:35], v[230:233], v[190:193], v[32:35]
	v_mfma_f32_16x16x32_bf16 v[52:55], v[222:225], v[198:201], v[52:55]
	v_mfma_f32_16x16x32_bf16 v[60:63], v[230:233], v[198:201], v[60:63]
	v_mfma_f32_16x16x32_bf16 v[80:83], v[222:225], v[206:209], v[80:83]
	v_mfma_f32_16x16x32_bf16 v[88:91], v[230:233], v[206:209], v[88:91]
	v_mfma_f32_16x16x32_bf16 v[100:103], v[222:225], v[214:217], v[100:103]
	v_mfma_f32_16x16x32_bf16 v[112:115], v[230:233], v[214:217], v[112:115]
	s_setprio 0
	s_barrier
